# v35 + s_nop padding so every 32-MFMA run starts 8-byte aligned
# baseline (speedup 1.0000x reference)
.LBB0_131:
	s_add_u32 s8, s2, 0xfff00080
	s_addc_u32 s9, s3, -1
	s_add_i32 s27, 0, 0x10000
	s_cmp_eq_u32 s26, 60
	s_cselect_b32 s11, s5, s9
	s_cselect_b32 s10, s7, s8
	v_add_u32_e32 v148, s27, v153
	s_cselect_b32 s9, s12, s25
	s_cselect_b32 s8, s13, s24
	s_add_i32 s30, 0, 0x14000
	ds_read_b128 v[140:143], v148
	ds_read_b128 v[144:147], v148 offset:1024
	ds_read_b128 v[156:159], v148 offset:2048
	ds_read_b128 v[160:163], v148 offset:3072
	v_add_u32_e32 v148, s30, v153
	ds_read_b128 v[164:167], v148
	ds_read_b128 v[180:183], v148 offset:1024
	ds_read_b128 v[184:187], v148 offset:2048
	ds_read_b128 v[188:191], v148 offset:3072
	v_lshl_add_u64 v[148:149], s[2:3], 0, v[136:137]
	s_add_i32 m0, s16, 0xc000
	ds_read_b128 v[192:195], v154
	ds_read_b128 v[196:199], v154 offset:1024
	ds_read_b128 v[200:203], v154 offset:2048
	ds_read_b128 v[204:207], v154 offset:3072
	ds_read_b128 v[218:221], v154 offset:4096
	ds_read_b128 v[222:225], v154 offset:5120
	ds_read_b128 v[226:229], v154 offset:6144
	ds_read_b128 v[230:233], v154 offset:7168
	global_load_lds_dwordx4 v[148:149], off
	v_lshl_add_u64 v[148:149], s[2:3], 0, v[138:139]
	s_add_i32 m0, s16, 0xe000
	s_nop 0
	global_load_lds_dwordx4 v[148:149], off
	s_waitcnt vmcnt(8)
	s_waitcnt lgkmcnt(0)
	s_barrier
	s_setprio 1
	s_waitcnt lgkmcnt(0)
	s_nop 0
	v_mfma_f32_16x16x32_bf16 v[126:129], v[140:143], v[192:195], v[126:129]
	v_mfma_f32_16x16x32_bf16 v[122:125], v[156:159], v[192:195], v[122:125]
	v_mfma_f32_16x16x32_bf16 v[110:113], v[140:143], v[200:203], v[110:113]
	v_mfma_f32_16x16x32_bf16 v[106:109], v[156:159], v[200:203], v[106:109]
	v_mfma_f32_16x16x32_bf16 v[94:97], v[140:143], v[218:221], v[94:97]
	v_mfma_f32_16x16x32_bf16 v[90:93], v[156:159], v[218:221], v[90:93]
	v_mfma_f32_16x16x32_bf16 v[78:81], v[140:143], v[226:229], v[78:81]
	v_mfma_f32_16x16x32_bf16 v[74:77], v[156:159], v[226:229], v[74:77]
	v_mfma_f32_16x16x32_bf16 v[118:121], v[164:167], v[192:195], v[118:121]
	v_mfma_f32_16x16x32_bf16 v[114:117], v[184:187], v[192:195], v[114:117]
	v_mfma_f32_16x16x32_bf16 v[102:105], v[164:167], v[200:203], v[102:105]
	v_mfma_f32_16x16x32_bf16 v[98:101], v[184:187], v[200:203], v[98:101]
	v_mfma_f32_16x16x32_bf16 v[86:89], v[164:167], v[218:221], v[86:89]
	v_mfma_f32_16x16x32_bf16 v[82:85], v[184:187], v[218:221], v[82:85]
	v_mfma_f32_16x16x32_bf16 v[70:73], v[164:167], v[226:229], v[70:73]
	v_mfma_f32_16x16x32_bf16 v[66:69], v[184:187], v[226:229], v[66:69]
	v_mfma_f32_16x16x32_bf16 v[126:129], v[144:147], v[196:199], v[126:129]
	v_mfma_f32_16x16x32_bf16 v[122:125], v[160:163], v[196:199], v[122:125]
	v_mfma_f32_16x16x32_bf16 v[110:113], v[144:147], v[204:207], v[110:113]
	v_mfma_f32_16x16x32_bf16 v[106:109], v[160:163], v[204:207], v[106:109]
	v_mfma_f32_16x16x32_bf16 v[94:97], v[144:147], v[222:225], v[94:97]
	v_mfma_f32_16x16x32_bf16 v[90:93], v[160:163], v[222:225], v[90:93]
	v_mfma_f32_16x16x32_bf16 v[78:81], v[144:147], v[230:233], v[78:81]
	v_mfma_f32_16x16x32_bf16 v[74:77], v[160:163], v[230:233], v[74:77]
	v_mfma_f32_16x16x32_bf16 v[118:121], v[180:183], v[196:199], v[118:121]
	v_mfma_f32_16x16x32_bf16 v[114:117], v[188:191], v[196:199], v[114:117]
	v_mfma_f32_16x16x32_bf16 v[102:105], v[180:183], v[204:207], v[102:105]
	v_mfma_f32_16x16x32_bf16 v[98:101], v[188:191], v[204:207], v[98:101]
	v_mfma_f32_16x16x32_bf16 v[86:89], v[180:183], v[222:225], v[86:89]
	v_mfma_f32_16x16x32_bf16 v[82:85], v[188:191], v[222:225], v[82:85]
	v_mfma_f32_16x16x32_bf16 v[70:73], v[180:183], v[230:233], v[70:73]
	v_mfma_f32_16x16x32_bf16 v[66:69], v[188:191], v[230:233], v[66:69]
	s_setprio 0
	s_barrier
	s_add_i32 s27, s27, s83
	v_lshl_add_u64 v[148:149], s[8:9], 0, v[0:1]
	s_mov_b32 m0, s27
	ds_read_b128 v[192:195], v154 offset:16384
	ds_read_b128 v[196:199], v154 offset:17408
	ds_read_b128 v[200:203], v154 offset:18432
	ds_read_b128 v[204:207], v154 offset:19456
	ds_read_b128 v[218:221], v154 offset:20480
	ds_read_b128 v[222:225], v154 offset:21504
	ds_read_b128 v[226:229], v154 offset:22528
	ds_read_b128 v[230:233], v154 offset:23552
	global_load_lds_dwordx4 v[148:149], off
	s_add_i32 m0, s27, 0x2000
	s_add_u32 s28, s8, 0x100000
	v_lshl_add_u64 v[168:169], s[8:9], 0, v[134:135]
	s_addc_u32 s29, s9, 0
	s_add_i32 s27, s30, s83
	global_load_lds_dwordx4 v[168:169], off
	v_lshl_add_u64 v[208:209], s[28:29], 0, v[0:1]
	s_mov_b32 m0, s27
	v_lshl_add_u64 v[234:235], s[10:11], 0, v[132:133]
	global_load_lds_dwordx4 v[208:209], off
	v_lshl_add_u64 v[208:209], s[28:29], 0, v[134:135]
	s_add_i32 m0, s27, 0x2000
	s_nop 0
	global_load_lds_dwordx4 v[208:209], off
	v_lshl_add_u64 v[208:209], s[10:11], 0, v[130:131]
	s_mov_b32 m0, s16
	s_nop 0
	global_load_lds_dwordx4 v[208:209], off
	s_mov_b32 m0, s17
	s_nop 0
	global_load_lds_dwordx4 v[234:235], off
	s_waitcnt vmcnt(8)
	s_waitcnt lgkmcnt(0)
	s_barrier
	s_setprio 1
	s_waitcnt lgkmcnt(0)
	s_nop 0
	v_mfma_f32_16x16x32_bf16 v[62:65], v[140:143], v[192:195], v[62:65]
	v_mfma_f32_16x16x32_bf16 v[58:61], v[156:159], v[192:195], v[58:61]
	v_mfma_f32_16x16x32_bf16 v[46:49], v[140:143], v[200:203], v[46:49]
	v_mfma_f32_16x16x32_bf16 v[42:45], v[156:159], v[200:203], v[42:45]
	v_mfma_f32_16x16x32_bf16 v[30:33], v[140:143], v[218:221], v[30:33]
	v_mfma_f32_16x16x32_bf16 v[26:29], v[156:159], v[218:221], v[26:29]
	v_mfma_f32_16x16x32_bf16 v[14:17], v[140:143], v[226:229], v[14:17]
	v_mfma_f32_16x16x32_bf16 v[10:13], v[156:159], v[226:229], v[10:13]
	v_mfma_f32_16x16x32_bf16 v[54:57], v[164:167], v[192:195], v[54:57]
	v_mfma_f32_16x16x32_bf16 v[50:53], v[184:187], v[192:195], v[50:53]
	v_mfma_f32_16x16x32_bf16 v[38:41], v[164:167], v[200:203], v[38:41]
	v_mfma_f32_16x16x32_bf16 v[34:37], v[184:187], v[200:203], v[34:37]
	v_mfma_f32_16x16x32_bf16 v[22:25], v[164:167], v[218:221], v[22:25]
	v_mfma_f32_16x16x32_bf16 v[18:21], v[184:187], v[218:221], v[18:21]
	v_mfma_f32_16x16x32_bf16 v[6:9], v[164:167], v[226:229], v[6:9]
	v_mfma_f32_16x16x32_bf16 v[2:5], v[184:187], v[226:229], v[2:5]
	v_mfma_f32_16x16x32_bf16 v[62:65], v[144:147], v[196:199], v[62:65]
	v_mfma_f32_16x16x32_bf16 v[58:61], v[160:163], v[196:199], v[58:61]
	v_mfma_f32_16x16x32_bf16 v[46:49], v[144:147], v[204:207], v[46:49]
	v_mfma_f32_16x16x32_bf16 v[42:45], v[160:163], v[204:207], v[42:45]
	v_mfma_f32_16x16x32_bf16 v[30:33], v[144:147], v[222:225], v[30:33]
	v_mfma_f32_16x16x32_bf16 v[26:29], v[160:163], v[222:225], v[26:29]
	v_mfma_f32_16x16x32_bf16 v[14:17], v[144:147], v[230:233], v[14:17]
	v_mfma_f32_16x16x32_bf16 v[10:13], v[160:163], v[230:233], v[10:13]
	v_mfma_f32_16x16x32_bf16 v[54:57], v[180:183], v[196:199], v[54:57]
	v_mfma_f32_16x16x32_bf16 v[50:53], v[188:191], v[196:199], v[50:53]
	v_mfma_f32_16x16x32_bf16 v[38:41], v[180:183], v[204:207], v[38:41]
	v_mfma_f32_16x16x32_bf16 v[34:37], v[188:191], v[204:207], v[34:37]
	v_mfma_f32_16x16x32_bf16 v[22:25], v[180:183], v[222:225], v[22:25]
	v_mfma_f32_16x16x32_bf16 v[18:21], v[188:191], v[222:225], v[18:21]
	v_mfma_f32_16x16x32_bf16 v[6:9], v[180:183], v[230:233], v[6:9]
	v_mfma_f32_16x16x32_bf16 v[2:5], v[188:191], v[230:233], v[2:5]
	s_setprio 0
	s_barrier
	s_add_i32 s27, 0, 0x18000
	v_add_u32_e32 v155, s27, v153
	s_add_i32 s28, 0, 0x1c000
	ds_read_b128 v[140:143], v155
	ds_read_b128 v[144:147], v155 offset:1024
	ds_read_b128 v[156:159], v155 offset:2048
	ds_read_b128 v[160:163], v155 offset:3072
	v_add_u32_e32 v155, s28, v153
	ds_read_b128 v[164:167], v155
	ds_read_b128 v[180:183], v155 offset:1024
	ds_read_b128 v[184:187], v155 offset:2048
	ds_read_b128 v[188:191], v155 offset:3072
	s_add_u32 s10, s10, 0x100000
	s_addc_u32 s11, s11, 0
	s_mov_b32 m0, s53
	v_lshl_add_u64 v[236:237], s[10:11], 0, v[130:131]
	ds_read_b128 v[192:195], v154 offset:32768
	ds_read_b128 v[196:199], v154 offset:33792
	ds_read_b128 v[200:203], v154 offset:34816
	ds_read_b128 v[204:207], v154 offset:35840
	ds_read_b128 v[218:221], v154 offset:36864
	ds_read_b128 v[222:225], v154 offset:37888
	ds_read_b128 v[226:229], v154 offset:38912
	ds_read_b128 v[230:233], v154 offset:39936
	global_load_lds_dwordx4 v[236:237], off
	v_lshl_add_u64 v[236:237], s[10:11], 0, v[132:133]
	s_mov_b32 m0, s57
	s_nop 0
	global_load_lds_dwordx4 v[236:237], off
	s_waitcnt vmcnt(8)
	s_waitcnt lgkmcnt(0)
	s_barrier
	s_setprio 1
	s_waitcnt lgkmcnt(0)
	s_nop 0
	v_mfma_f32_16x16x32_bf16 v[126:129], v[140:143], v[192:195], v[126:129]
	v_mfma_f32_16x16x32_bf16 v[122:125], v[156:159], v[192:195], v[122:125]
	v_mfma_f32_16x16x32_bf16 v[110:113], v[140:143], v[200:203], v[110:113]
	v_mfma_f32_16x16x32_bf16 v[106:109], v[156:159], v[200:203], v[106:109]
	v_mfma_f32_16x16x32_bf16 v[94:97], v[140:143], v[218:221], v[94:97]
	v_mfma_f32_16x16x32_bf16 v[90:93], v[156:159], v[218:221], v[90:93]
	v_mfma_f32_16x16x32_bf16 v[78:81], v[140:143], v[226:229], v[78:81]
	v_mfma_f32_16x16x32_bf16 v[74:77], v[156:159], v[226:229], v[74:77]
	v_mfma_f32_16x16x32_bf16 v[118:121], v[164:167], v[192:195], v[118:121]
	v_mfma_f32_16x16x32_bf16 v[114:117], v[184:187], v[192:195], v[114:117]
	v_mfma_f32_16x16x32_bf16 v[102:105], v[164:167], v[200:203], v[102:105]
	v_mfma_f32_16x16x32_bf16 v[98:101], v[184:187], v[200:203], v[98:101]
	v_mfma_f32_16x16x32_bf16 v[86:89], v[164:167], v[218:221], v[86:89]
	v_mfma_f32_16x16x32_bf16 v[82:85], v[184:187], v[218:221], v[82:85]
	v_mfma_f32_16x16x32_bf16 v[70:73], v[164:167], v[226:229], v[70:73]
	v_mfma_f32_16x16x32_bf16 v[66:69], v[184:187], v[226:229], v[66:69]
	v_mfma_f32_16x16x32_bf16 v[126:129], v[144:147], v[196:199], v[126:129]
	v_mfma_f32_16x16x32_bf16 v[122:125], v[160:163], v[196:199], v[122:125]
	v_mfma_f32_16x16x32_bf16 v[110:113], v[144:147], v[204:207], v[110:113]
	v_mfma_f32_16x16x32_bf16 v[106:109], v[160:163], v[204:207], v[106:109]
	v_mfma_f32_16x16x32_bf16 v[94:97], v[144:147], v[222:225], v[94:97]
	v_mfma_f32_16x16x32_bf16 v[90:93], v[160:163], v[222:225], v[90:93]
	v_mfma_f32_16x16x32_bf16 v[78:81], v[144:147], v[230:233], v[78:81]
	v_mfma_f32_16x16x32_bf16 v[74:77], v[160:163], v[230:233], v[74:77]
	v_mfma_f32_16x16x32_bf16 v[118:121], v[180:183], v[196:199], v[118:121]
	v_mfma_f32_16x16x32_bf16 v[114:117], v[188:191], v[196:199], v[114:117]
	v_mfma_f32_16x16x32_bf16 v[102:105], v[180:183], v[204:207], v[102:105]
	v_mfma_f32_16x16x32_bf16 v[98:101], v[188:191], v[204:207], v[98:101]
	v_mfma_f32_16x16x32_bf16 v[86:89], v[180:183], v[222:225], v[86:89]
	v_mfma_f32_16x16x32_bf16 v[82:85], v[188:191], v[222:225], v[82:85]
	v_mfma_f32_16x16x32_bf16 v[70:73], v[180:183], v[230:233], v[70:73]
	v_mfma_f32_16x16x32_bf16 v[66:69], v[188:191], v[230:233], v[66:69]
	s_setprio 0
	s_barrier
	s_add_i32 s10, s27, s83
	v_lshl_add_u64 v[148:149], v[148:149], 0, s[88:89]
	s_mov_b32 m0, s10
	ds_read_b128 v[192:195], v154 offset:49152
	ds_read_b128 v[196:199], v154 offset:50176
	ds_read_b128 v[200:203], v154 offset:51200
	ds_read_b128 v[204:207], v154 offset:52224
	ds_read_b128 v[218:221], v154 offset:53248
	ds_read_b128 v[222:225], v154 offset:54272
	ds_read_b128 v[226:229], v154 offset:55296
	ds_read_b128 v[230:233], v154 offset:56320
	global_load_lds_dwordx4 v[148:149], off
	s_add_i32 m0, s10, 0x2000
	s_add_u32 s8, s8, 0x100080
	v_lshl_add_u64 v[148:149], v[168:169], 0, s[88:89]
	s_addc_u32 s9, s9, 0
	s_add_i32 s10, s28, s83
	global_load_lds_dwordx4 v[148:149], off
	v_lshl_add_u64 v[148:149], s[8:9], 0, v[0:1]
	s_mov_b32 m0, s10
	s_nop 0
	global_load_lds_dwordx4 v[148:149], off
	v_lshl_add_u64 v[148:149], s[8:9], 0, v[134:135]
	s_add_i32 m0, s10, 0x2000
	s_nop 0
	global_load_lds_dwordx4 v[148:149], off
	v_lshl_add_u64 v[148:149], v[208:209], 0, s[88:89]
	s_mov_b32 m0, s52
	s_nop 0
	global_load_lds_dwordx4 v[148:149], off
	v_lshl_add_u64 v[148:149], v[234:235], 0, s[88:89]
	s_mov_b32 m0, s90
	s_nop 0
	global_load_lds_dwordx4 v[148:149], off
	s_waitcnt vmcnt(8)
	s_waitcnt lgkmcnt(0)
	s_barrier
	s_setprio 1
	s_waitcnt lgkmcnt(0)
	v_mfma_f32_16x16x32_bf16 v[62:65], v[140:143], v[192:195], v[62:65]
	v_mfma_f32_16x16x32_bf16 v[58:61], v[156:159], v[192:195], v[58:61]
	v_mfma_f32_16x16x32_bf16 v[46:49], v[140:143], v[200:203], v[46:49]
	v_mfma_f32_16x16x32_bf16 v[42:45], v[156:159], v[200:203], v[42:45]
	v_mfma_f32_16x16x32_bf16 v[30:33], v[140:143], v[218:221], v[30:33]
	v_mfma_f32_16x16x32_bf16 v[26:29], v[156:159], v[218:221], v[26:29]
	v_mfma_f32_16x16x32_bf16 v[14:17], v[140:143], v[226:229], v[14:17]
	v_mfma_f32_16x16x32_bf16 v[10:13], v[156:159], v[226:229], v[10:13]
	v_mfma_f32_16x16x32_bf16 v[54:57], v[164:167], v[192:195], v[54:57]
	v_mfma_f32_16x16x32_bf16 v[50:53], v[184:187], v[192:195], v[50:53]
	v_mfma_f32_16x16x32_bf16 v[38:41], v[164:167], v[200:203], v[38:41]
	v_mfma_f32_16x16x32_bf16 v[34:37], v[184:187], v[200:203], v[34:37]
	v_mfma_f32_16x16x32_bf16 v[22:25], v[164:167], v[218:221], v[22:25]
	v_mfma_f32_16x16x32_bf16 v[18:21], v[184:187], v[218:221], v[18:21]
	v_mfma_f32_16x16x32_bf16 v[6:9], v[164:167], v[226:229], v[6:9]
	v_mfma_f32_16x16x32_bf16 v[2:5], v[184:187], v[226:229], v[2:5]
	v_mfma_f32_16x16x32_bf16 v[62:65], v[144:147], v[196:199], v[62:65]
	v_mfma_f32_16x16x32_bf16 v[58:61], v[160:163], v[196:199], v[58:61]
	v_mfma_f32_16x16x32_bf16 v[46:49], v[144:147], v[204:207], v[46:49]
	v_mfma_f32_16x16x32_bf16 v[42:45], v[160:163], v[204:207], v[42:45]
	v_mfma_f32_16x16x32_bf16 v[30:33], v[144:147], v[222:225], v[30:33]
	v_mfma_f32_16x16x32_bf16 v[26:29], v[160:163], v[222:225], v[26:29]
	v_mfma_f32_16x16x32_bf16 v[14:17], v[144:147], v[230:233], v[14:17]
	v_mfma_f32_16x16x32_bf16 v[10:13], v[160:163], v[230:233], v[10:13]
	v_mfma_f32_16x16x32_bf16 v[54:57], v[180:183], v[196:199], v[54:57]
	v_mfma_f32_16x16x32_bf16 v[50:53], v[188:191], v[196:199], v[50:53]
	v_mfma_f32_16x16x32_bf16 v[38:41], v[180:183], v[204:207], v[38:41]
	v_mfma_f32_16x16x32_bf16 v[34:37], v[188:191], v[204:207], v[34:37]
	v_mfma_f32_16x16x32_bf16 v[22:25], v[180:183], v[222:225], v[22:25]
	v_mfma_f32_16x16x32_bf16 v[18:21], v[188:191], v[222:225], v[18:21]
	v_mfma_f32_16x16x32_bf16 v[6:9], v[180:183], v[230:233], v[6:9]
	v_mfma_f32_16x16x32_bf16 v[2:5], v[188:191], v[230:233], v[2:5]
	s_setprio 0
	s_barrier
	s_add_i32 s26, s26, 2
	s_add_u32 s2, s2, 0x100
	s_addc_u32 s3, s3, 0
	s_add_u32 s24, s24, 0x100
	s_addc_u32 s25, s25, 0
	s_cmp_gt_u32 s26, 61
	s_cbranch_scc0 .LBB0_131
	s_and_b64 vcc, exec, s[94:95]
	s_cbranch_vccz .LBB0_134
	s_barrier

.LBB0_735:
	s_add_u32 s17, s10, s2
	s_addc_u32 s19, s11, s3
	s_add_u32 s36, s4, s2
	s_addc_u32 s37, s5, s3
	s_add_i32 s60, 0, 0x10000
	s_cmp_eq_u32 s31, s13
	s_cselect_b32 s73, s65, s19
	s_cselect_b32 s72, s64, s17
	v_add_u32_e32 v148, s60, v152
	s_cselect_b32 s71, s67, s37
	s_cselect_b32 s70, s66, s36
	s_add_i32 s54, 0, 0x14000
	ds_read_b128 v[144:147], v148
	ds_read_b128 v[154:157], v148 offset:1024
	ds_read_b128 v[158:161], v148 offset:2048
	ds_read_b128 v[162:165], v148 offset:3072
	v_add_u32_e32 v148, s54, v152
	ds_read_b128 v[166:169], v148
	ds_read_b128 v[180:183], v148 offset:1024
	ds_read_b128 v[184:187], v148 offset:2048
	ds_read_b128 v[188:191], v148 offset:3072
	v_lshl_add_u64 v[148:149], s[10:11], 0, v[132:133]
	s_add_i32 m0, s23, 0xc000
	ds_read_b128 v[192:195], v153
	ds_read_b128 v[196:199], v153 offset:1024
	ds_read_b128 v[200:203], v153 offset:2048
	ds_read_b128 v[204:207], v153 offset:3072
	ds_read_b128 v[218:221], v153 offset:4096
	ds_read_b128 v[222:225], v153 offset:5120
	ds_read_b128 v[226:229], v153 offset:6144
	ds_read_b128 v[230:233], v153 offset:7168
	global_load_lds_dwordx4 v[148:149], off
	v_lshl_add_u64 v[148:149], s[10:11], 0, v[130:131]
	s_add_i32 m0, s23, 0xe000
	s_nop 0
	global_load_lds_dwordx4 v[148:149], off
	s_waitcnt vmcnt(8)
	s_waitcnt lgkmcnt(0)
	s_barrier
	s_setprio 1
	s_waitcnt lgkmcnt(0)
	s_nop 0
	v_mfma_f32_16x16x32_bf16 v[126:129], v[144:147], v[192:195], v[126:129]
	v_mfma_f32_16x16x32_bf16 v[122:125], v[158:161], v[192:195], v[122:125]
	v_mfma_f32_16x16x32_bf16 v[118:121], v[144:147], v[200:203], v[118:121]
	v_mfma_f32_16x16x32_bf16 v[114:117], v[158:161], v[200:203], v[114:117]
	v_mfma_f32_16x16x32_bf16 v[110:113], v[144:147], v[218:221], v[110:113]
	v_mfma_f32_16x16x32_bf16 v[106:109], v[158:161], v[218:221], v[106:109]
	v_mfma_f32_16x16x32_bf16 v[102:105], v[144:147], v[226:229], v[102:105]
	v_mfma_f32_16x16x32_bf16 v[98:101], v[158:161], v[226:229], v[98:101]
	v_mfma_f32_16x16x32_bf16 v[94:97], v[166:169], v[192:195], v[94:97]
	v_mfma_f32_16x16x32_bf16 v[90:93], v[184:187], v[192:195], v[90:93]
	v_mfma_f32_16x16x32_bf16 v[86:89], v[166:169], v[200:203], v[86:89]
	v_mfma_f32_16x16x32_bf16 v[82:85], v[184:187], v[200:203], v[82:85]
	v_mfma_f32_16x16x32_bf16 v[78:81], v[166:169], v[218:221], v[78:81]
	v_mfma_f32_16x16x32_bf16 v[74:77], v[184:187], v[218:221], v[74:77]
	v_mfma_f32_16x16x32_bf16 v[70:73], v[166:169], v[226:229], v[70:73]
	v_mfma_f32_16x16x32_bf16 v[66:69], v[184:187], v[226:229], v[66:69]
	v_mfma_f32_16x16x32_bf16 v[126:129], v[154:157], v[196:199], v[126:129]
	v_mfma_f32_16x16x32_bf16 v[122:125], v[162:165], v[196:199], v[122:125]
	v_mfma_f32_16x16x32_bf16 v[118:121], v[154:157], v[204:207], v[118:121]
	v_mfma_f32_16x16x32_bf16 v[114:117], v[162:165], v[204:207], v[114:117]
	v_mfma_f32_16x16x32_bf16 v[110:113], v[154:157], v[222:225], v[110:113]
	v_mfma_f32_16x16x32_bf16 v[106:109], v[162:165], v[222:225], v[106:109]
	v_mfma_f32_16x16x32_bf16 v[102:105], v[154:157], v[230:233], v[102:105]
	v_mfma_f32_16x16x32_bf16 v[98:101], v[162:165], v[230:233], v[98:101]
	v_mfma_f32_16x16x32_bf16 v[94:97], v[180:183], v[196:199], v[94:97]
	v_mfma_f32_16x16x32_bf16 v[90:93], v[188:191], v[196:199], v[90:93]
	v_mfma_f32_16x16x32_bf16 v[86:89], v[180:183], v[204:207], v[86:89]
	v_mfma_f32_16x16x32_bf16 v[82:85], v[188:191], v[204:207], v[82:85]
	v_mfma_f32_16x16x32_bf16 v[78:81], v[180:183], v[222:225], v[78:81]
	v_mfma_f32_16x16x32_bf16 v[74:77], v[188:191], v[222:225], v[74:77]
	v_mfma_f32_16x16x32_bf16 v[70:73], v[180:183], v[230:233], v[70:73]
	v_mfma_f32_16x16x32_bf16 v[66:69], v[188:191], v[230:233], v[66:69]
	s_setprio 0
	s_barrier
	s_add_i32 s17, s60, s22
	v_lshl_add_u64 v[148:149], s[70:71], 0, v[0:1]
	s_mov_b32 m0, s17
	ds_read_b128 v[192:195], v153 offset:16384
	ds_read_b128 v[196:199], v153 offset:17408
	ds_read_b128 v[200:203], v153 offset:18432
	ds_read_b128 v[204:207], v153 offset:19456
	ds_read_b128 v[218:221], v153 offset:20480
	ds_read_b128 v[222:225], v153 offset:21504
	ds_read_b128 v[226:229], v153 offset:22528
	ds_read_b128 v[230:233], v153 offset:23552
	global_load_lds_dwordx4 v[148:149], off
	s_add_i32 m0, s17, 0x2000
	s_add_u32 s36, s70, 0x100000
	v_lshl_add_u64 v[208:209], s[70:71], 0, v[138:139]
	s_addc_u32 s37, s71, 0
	s_add_i32 s17, s54, s22
	global_load_lds_dwordx4 v[208:209], off
	v_lshl_add_u64 v[234:235], s[36:37], 0, v[0:1]
	s_mov_b32 m0, s17
	v_lshl_add_u64 v[236:237], s[72:73], 0, v[136:137]
	global_load_lds_dwordx4 v[234:235], off
	v_lshl_add_u64 v[234:235], s[36:37], 0, v[138:139]
	s_add_i32 m0, s17, 0x2000
	s_nop 0
	global_load_lds_dwordx4 v[234:235], off
	v_lshl_add_u64 v[234:235], s[72:73], 0, v[134:135]
	s_mov_b32 m0, s23
	s_nop 0
	global_load_lds_dwordx4 v[234:235], off
	s_mov_b32 m0, s24
	s_nop 0
	global_load_lds_dwordx4 v[236:237], off
	s_waitcnt vmcnt(8)
	s_waitcnt lgkmcnt(0)
	s_barrier
	s_setprio 1
	s_waitcnt lgkmcnt(0)
	s_nop 0
	v_mfma_f32_16x16x32_bf16 v[62:65], v[144:147], v[192:195], v[62:65]
	v_mfma_f32_16x16x32_bf16 v[58:61], v[158:161], v[192:195], v[58:61]
	v_mfma_f32_16x16x32_bf16 v[54:57], v[144:147], v[200:203], v[54:57]
	v_mfma_f32_16x16x32_bf16 v[50:53], v[158:161], v[200:203], v[50:53]
	v_mfma_f32_16x16x32_bf16 v[46:49], v[144:147], v[218:221], v[46:49]
	v_mfma_f32_16x16x32_bf16 v[42:45], v[158:161], v[218:221], v[42:45]
	v_mfma_f32_16x16x32_bf16 v[38:41], v[144:147], v[226:229], v[38:41]
	v_mfma_f32_16x16x32_bf16 v[34:37], v[158:161], v[226:229], v[34:37]
	v_mfma_f32_16x16x32_bf16 v[30:33], v[166:169], v[192:195], v[30:33]
	v_mfma_f32_16x16x32_bf16 v[26:29], v[184:187], v[192:195], v[26:29]
	v_mfma_f32_16x16x32_bf16 v[22:25], v[166:169], v[200:203], v[22:25]
	v_mfma_f32_16x16x32_bf16 v[18:21], v[184:187], v[200:203], v[18:21]
	v_mfma_f32_16x16x32_bf16 v[14:17], v[166:169], v[218:221], v[14:17]
	v_mfma_f32_16x16x32_bf16 v[10:13], v[184:187], v[218:221], v[10:13]
	v_mfma_f32_16x16x32_bf16 v[6:9], v[166:169], v[226:229], v[6:9]
	v_mfma_f32_16x16x32_bf16 v[2:5], v[184:187], v[226:229], v[2:5]
	v_mfma_f32_16x16x32_bf16 v[62:65], v[154:157], v[196:199], v[62:65]
	v_mfma_f32_16x16x32_bf16 v[58:61], v[162:165], v[196:199], v[58:61]
	v_mfma_f32_16x16x32_bf16 v[54:57], v[154:157], v[204:207], v[54:57]
	v_mfma_f32_16x16x32_bf16 v[50:53], v[162:165], v[204:207], v[50:53]
	v_mfma_f32_16x16x32_bf16 v[46:49], v[154:157], v[222:225], v[46:49]
	v_mfma_f32_16x16x32_bf16 v[42:45], v[162:165], v[222:225], v[42:45]
	v_mfma_f32_16x16x32_bf16 v[38:41], v[154:157], v[230:233], v[38:41]
	v_mfma_f32_16x16x32_bf16 v[34:37], v[162:165], v[230:233], v[34:37]
	v_mfma_f32_16x16x32_bf16 v[30:33], v[180:183], v[196:199], v[30:33]
	v_mfma_f32_16x16x32_bf16 v[26:29], v[188:191], v[196:199], v[26:29]
	v_mfma_f32_16x16x32_bf16 v[22:25], v[180:183], v[204:207], v[22:25]
	v_mfma_f32_16x16x32_bf16 v[18:21], v[188:191], v[204:207], v[18:21]
	v_mfma_f32_16x16x32_bf16 v[14:17], v[180:183], v[222:225], v[14:17]
	v_mfma_f32_16x16x32_bf16 v[10:13], v[188:191], v[222:225], v[10:13]
	v_mfma_f32_16x16x32_bf16 v[6:9], v[180:183], v[230:233], v[6:9]
	v_mfma_f32_16x16x32_bf16 v[2:5], v[188:191], v[230:233], v[2:5]
	s_setprio 0
	s_barrier
	s_add_i32 s61, 0, 0x18000
	s_add_i32 s62, 0, 0x1c000
	v_add_u32_e32 v162, s61, v152
	v_add_u32_e32 v170, s62, v152
	ds_read_b128 v[144:147], v162
	ds_read_b128 v[154:157], v162 offset:1024
	ds_read_b128 v[158:161], v162 offset:2048
	ds_read_b128 v[162:165], v162 offset:3072
	ds_read_b128 v[166:169], v170
	ds_read_b128 v[180:183], v170 offset:1024
	ds_read_b128 v[184:187], v170 offset:2048
	ds_read_b128 v[188:191], v170 offset:3072
	s_add_u32 s36, s72, 0x100000
	s_addc_u32 s37, s73, 0
	s_mov_b32 m0, s25
	v_lshl_add_u64 v[238:239], s[36:37], 0, v[134:135]
	ds_read_b128 v[192:195], v153 offset:32768
	ds_read_b128 v[196:199], v153 offset:33792
	ds_read_b128 v[200:203], v153 offset:34816
	ds_read_b128 v[204:207], v153 offset:35840
	ds_read_b128 v[218:221], v153 offset:36864
	ds_read_b128 v[222:225], v153 offset:37888
	ds_read_b128 v[226:229], v153 offset:38912
	ds_read_b128 v[230:233], v153 offset:39936
	global_load_lds_dwordx4 v[238:239], off
	v_lshl_add_u64 v[238:239], s[36:37], 0, v[136:137]
	s_mov_b32 m0, s26
	s_nop 0
	global_load_lds_dwordx4 v[238:239], off
	s_waitcnt vmcnt(8)
	s_waitcnt lgkmcnt(0)
	s_barrier
	s_setprio 1
	s_waitcnt lgkmcnt(0)
	s_nop 0
	v_mfma_f32_16x16x32_bf16 v[126:129], v[144:147], v[192:195], v[126:129]
	v_mfma_f32_16x16x32_bf16 v[122:125], v[158:161], v[192:195], v[122:125]
	v_mfma_f32_16x16x32_bf16 v[118:121], v[144:147], v[200:203], v[118:121]
	v_mfma_f32_16x16x32_bf16 v[114:117], v[158:161], v[200:203], v[114:117]
	v_mfma_f32_16x16x32_bf16 v[110:113], v[144:147], v[218:221], v[110:113]
	v_mfma_f32_16x16x32_bf16 v[106:109], v[158:161], v[218:221], v[106:109]
	v_mfma_f32_16x16x32_bf16 v[102:105], v[144:147], v[226:229], v[102:105]
	v_mfma_f32_16x16x32_bf16 v[98:101], v[158:161], v[226:229], v[98:101]
	v_mfma_f32_16x16x32_bf16 v[94:97], v[166:169], v[192:195], v[94:97]
	v_mfma_f32_16x16x32_bf16 v[90:93], v[184:187], v[192:195], v[90:93]
	v_mfma_f32_16x16x32_bf16 v[86:89], v[166:169], v[200:203], v[86:89]
	v_mfma_f32_16x16x32_bf16 v[82:85], v[184:187], v[200:203], v[82:85]
	v_mfma_f32_16x16x32_bf16 v[78:81], v[166:169], v[218:221], v[78:81]
	v_mfma_f32_16x16x32_bf16 v[74:77], v[184:187], v[218:221], v[74:77]
	v_mfma_f32_16x16x32_bf16 v[70:73], v[166:169], v[226:229], v[70:73]
	v_mfma_f32_16x16x32_bf16 v[66:69], v[184:187], v[226:229], v[66:69]
	v_mfma_f32_16x16x32_bf16 v[126:129], v[154:157], v[196:199], v[126:129]
	v_mfma_f32_16x16x32_bf16 v[122:125], v[162:165], v[196:199], v[122:125]
	v_mfma_f32_16x16x32_bf16 v[118:121], v[154:157], v[204:207], v[118:121]
	v_mfma_f32_16x16x32_bf16 v[114:117], v[162:165], v[204:207], v[114:117]
	v_mfma_f32_16x16x32_bf16 v[110:113], v[154:157], v[222:225], v[110:113]
	v_mfma_f32_16x16x32_bf16 v[106:109], v[162:165], v[222:225], v[106:109]
	v_mfma_f32_16x16x32_bf16 v[102:105], v[154:157], v[230:233], v[102:105]
	v_mfma_f32_16x16x32_bf16 v[98:101], v[162:165], v[230:233], v[98:101]
	v_mfma_f32_16x16x32_bf16 v[94:97], v[180:183], v[196:199], v[94:97]
	v_mfma_f32_16x16x32_bf16 v[90:93], v[188:191], v[196:199], v[90:93]
	v_mfma_f32_16x16x32_bf16 v[86:89], v[180:183], v[204:207], v[86:89]
	v_mfma_f32_16x16x32_bf16 v[82:85], v[188:191], v[204:207], v[82:85]
	v_mfma_f32_16x16x32_bf16 v[78:81], v[180:183], v[222:225], v[78:81]
	v_mfma_f32_16x16x32_bf16 v[74:77], v[188:191], v[222:225], v[74:77]
	v_mfma_f32_16x16x32_bf16 v[70:73], v[180:183], v[230:233], v[70:73]
	v_mfma_f32_16x16x32_bf16 v[66:69], v[188:191], v[230:233], v[66:69]
	s_setprio 0
	s_barrier
	s_add_i32 s17, s61, s22
	v_lshl_add_u64 v[148:149], v[148:149], 0, s[88:89]
	s_mov_b32 m0, s17
	ds_read_b128 v[192:195], v153 offset:49152
	ds_read_b128 v[196:199], v153 offset:50176
	ds_read_b128 v[200:203], v153 offset:51200
	ds_read_b128 v[204:207], v153 offset:52224
	ds_read_b128 v[218:221], v153 offset:53248
	ds_read_b128 v[222:225], v153 offset:54272
	ds_read_b128 v[226:229], v153 offset:55296
	ds_read_b128 v[230:233], v153 offset:56320
	global_load_lds_dwordx4 v[148:149], off
	s_add_i32 m0, s17, 0x2000
	s_add_u32 s36, s70, 0x100080
	v_lshl_add_u64 v[148:149], v[208:209], 0, s[88:89]
	s_addc_u32 s37, s71, 0
	s_add_i32 s17, s62, s22
	global_load_lds_dwordx4 v[148:149], off
	v_lshl_add_u64 v[148:149], s[36:37], 0, v[0:1]
	s_mov_b32 m0, s17
	s_nop 0
	global_load_lds_dwordx4 v[148:149], off
	v_lshl_add_u64 v[148:149], s[36:37], 0, v[138:139]
	s_add_i32 m0, s17, 0x2000
	s_nop 0
	global_load_lds_dwordx4 v[148:149], off
	v_lshl_add_u64 v[148:149], v[234:235], 0, s[88:89]
	s_mov_b32 m0, s29
	s_nop 0
	global_load_lds_dwordx4 v[148:149], off
	v_lshl_add_u64 v[148:149], v[236:237], 0, s[88:89]
	s_mov_b32 m0, s30
	s_nop 0
	global_load_lds_dwordx4 v[148:149], off
	s_waitcnt vmcnt(8)
	s_waitcnt lgkmcnt(0)
	s_barrier
	s_setprio 1
	s_waitcnt lgkmcnt(0)
	v_mfma_f32_16x16x32_bf16 v[62:65], v[144:147], v[192:195], v[62:65]
	v_mfma_f32_16x16x32_bf16 v[58:61], v[158:161], v[192:195], v[58:61]
	v_mfma_f32_16x16x32_bf16 v[54:57], v[144:147], v[200:203], v[54:57]
	v_mfma_f32_16x16x32_bf16 v[50:53], v[158:161], v[200:203], v[50:53]
	v_mfma_f32_16x16x32_bf16 v[46:49], v[144:147], v[218:221], v[46:49]
	v_mfma_f32_16x16x32_bf16 v[42:45], v[158:161], v[218:221], v[42:45]
	v_mfma_f32_16x16x32_bf16 v[38:41], v[144:147], v[226:229], v[38:41]
	v_mfma_f32_16x16x32_bf16 v[34:37], v[158:161], v[226:229], v[34:37]
	v_mfma_f32_16x16x32_bf16 v[30:33], v[166:169], v[192:195], v[30:33]
	v_mfma_f32_16x16x32_bf16 v[26:29], v[184:187], v[192:195], v[26:29]
	v_mfma_f32_16x16x32_bf16 v[22:25], v[166:169], v[200:203], v[22:25]
	v_mfma_f32_16x16x32_bf16 v[18:21], v[184:187], v[200:203], v[18:21]
	v_mfma_f32_16x16x32_bf16 v[14:17], v[166:169], v[218:221], v[14:17]
	v_mfma_f32_16x16x32_bf16 v[10:13], v[184:187], v[218:221], v[10:13]
	v_mfma_f32_16x16x32_bf16 v[6:9], v[166:169], v[226:229], v[6:9]
	v_mfma_f32_16x16x32_bf16 v[2:5], v[184:187], v[226:229], v[2:5]
	v_mfma_f32_16x16x32_bf16 v[62:65], v[154:157], v[196:199], v[62:65]
	v_mfma_f32_16x16x32_bf16 v[58:61], v[162:165], v[196:199], v[58:61]
	v_mfma_f32_16x16x32_bf16 v[54:57], v[154:157], v[204:207], v[54:57]
	v_mfma_f32_16x16x32_bf16 v[50:53], v[162:165], v[204:207], v[50:53]
	v_mfma_f32_16x16x32_bf16 v[46:49], v[154:157], v[222:225], v[46:49]
	v_mfma_f32_16x16x32_bf16 v[42:45], v[162:165], v[222:225], v[42:45]
	v_mfma_f32_16x16x32_bf16 v[38:41], v[154:157], v[230:233], v[38:41]
	v_mfma_f32_16x16x32_bf16 v[34:37], v[162:165], v[230:233], v[34:37]
	v_mfma_f32_16x16x32_bf16 v[30:33], v[180:183], v[196:199], v[30:33]
	v_mfma_f32_16x16x32_bf16 v[26:29], v[188:191], v[196:199], v[26:29]
	v_mfma_f32_16x16x32_bf16 v[22:25], v[180:183], v[204:207], v[22:25]
	v_mfma_f32_16x16x32_bf16 v[18:21], v[188:191], v[204:207], v[18:21]
	v_mfma_f32_16x16x32_bf16 v[14:17], v[180:183], v[222:225], v[14:17]
	v_mfma_f32_16x16x32_bf16 v[10:13], v[188:191], v[222:225], v[10:13]
	v_mfma_f32_16x16x32_bf16 v[6:9], v[180:183], v[230:233], v[6:9]
	v_mfma_f32_16x16x32_bf16 v[2:5], v[188:191], v[230:233], v[2:5]
	s_setprio 0
	s_barrier
	s_add_i32 s17, s13, 2
	s_add_u32 s2, s2, 0x100
	s_addc_u32 s3, s3, 0
	v_lshl_add_u64 v[132:133], v[132:133], 0, s[92:93]
	v_lshl_add_u64 v[130:131], v[130:131], 0, s[92:93]
	s_cmp_ge_i32 s13, s31
	s_mov_b32 s13, s17
	s_cbranch_scc0 .LBB0_735
	s_and_b64 vcc, exec, s[8:9]
	s_cbranch_vccz .LBB0_738
	s_barrier

.LBB0_883:
	v_add_u32_e32 v0, s60, v221
	ds_read_b128 v[130:133], v0
	ds_read_b128 v[134:137], v0 offset:1024
	ds_read_b128 v[138:141], v0 offset:2048
	ds_read_b128 v[142:145], v0 offset:3072
	v_add_u32_e32 v0, s54, v221
	ds_read_b128 v[146:149], v0
	ds_read_b128 v[150:153], v0 offset:1024
	ds_read_b128 v[154:157], v0 offset:2048
	ds_read_b128 v[158:161], v0 offset:3072
	s_add_u32 s4, s0, 0x100
	s_addc_u32 s5, s1, 0
	s_cmp_eq_u32 s37, 60
	s_cselect_b32 vcc_hi, s78, s5
	s_cselect_b32 vcc_lo, s79, s4
	s_cselect_b32 s7, s86, s36
	s_cselect_b32 s6, s97, s3
	v_lshl_add_u64 v[208:209], s[0:1], 0, v[188:189]
	s_add_i32 m0, s9, 0xc000
	ds_read_b128 v[162:165], v222
	ds_read_b128 v[166:169], v222 offset:1024
	ds_read_b128 v[192:195], v222 offset:2048
	ds_read_b128 v[196:199], v222 offset:3072
	ds_read_b128 v[200:203], v222 offset:4096
	ds_read_b128 v[204:207], v222 offset:5120
	ds_read_b128 v[224:227], v222 offset:6144
	ds_read_b128 v[228:231], v222 offset:7168
	global_load_lds_dwordx4 v[208:209], off
	v_lshl_add_u64 v[208:209], s[0:1], 0, v[190:191]
	s_add_i32 m0, s9, 0xe000
	s_nop 0
	global_load_lds_dwordx4 v[208:209], off
	s_waitcnt vmcnt(8)
	s_waitcnt lgkmcnt(0)
	s_barrier
	s_setprio 1
	s_waitcnt lgkmcnt(0)
	v_mfma_f32_16x16x32_bf16 v[118:121], v[130:133], v[162:165], v[118:121]
	v_mfma_f32_16x16x32_bf16 v[86:89], v[138:141], v[162:165], v[86:89]
	v_mfma_f32_16x16x32_bf16 v[114:117], v[130:133], v[192:195], v[114:117]
	v_mfma_f32_16x16x32_bf16 v[82:85], v[138:141], v[192:195], v[82:85]
	v_mfma_f32_16x16x32_bf16 v[126:129], v[130:133], v[200:203], v[126:129]
	v_mfma_f32_16x16x32_bf16 v[94:97], v[138:141], v[200:203], v[94:97]
	v_mfma_f32_16x16x32_bf16 v[122:125], v[130:133], v[224:227], v[122:125]
	v_mfma_f32_16x16x32_bf16 v[90:93], v[138:141], v[224:227], v[90:93]
	v_mfma_f32_16x16x32_bf16 v[110:113], v[146:149], v[162:165], v[110:113]
	v_mfma_f32_16x16x32_bf16 v[78:81], v[154:157], v[162:165], v[78:81]
	v_mfma_f32_16x16x32_bf16 v[106:109], v[146:149], v[192:195], v[106:109]
	v_mfma_f32_16x16x32_bf16 v[74:77], v[154:157], v[192:195], v[74:77]
	v_mfma_f32_16x16x32_bf16 v[102:105], v[146:149], v[200:203], v[102:105]
	v_mfma_f32_16x16x32_bf16 v[70:73], v[154:157], v[200:203], v[70:73]
	v_mfma_f32_16x16x32_bf16 v[98:101], v[146:149], v[224:227], v[98:101]
	v_mfma_f32_16x16x32_bf16 v[66:69], v[154:157], v[224:227], v[66:69]
	v_mfma_f32_16x16x32_bf16 v[118:121], v[134:137], v[166:169], v[118:121]
	v_mfma_f32_16x16x32_bf16 v[86:89], v[142:145], v[166:169], v[86:89]
	v_mfma_f32_16x16x32_bf16 v[114:117], v[134:137], v[196:199], v[114:117]
	v_mfma_f32_16x16x32_bf16 v[82:85], v[142:145], v[196:199], v[82:85]
	v_mfma_f32_16x16x32_bf16 v[126:129], v[134:137], v[204:207], v[126:129]
	v_mfma_f32_16x16x32_bf16 v[94:97], v[142:145], v[204:207], v[94:97]
	v_mfma_f32_16x16x32_bf16 v[122:125], v[134:137], v[228:231], v[122:125]
	v_mfma_f32_16x16x32_bf16 v[90:93], v[142:145], v[228:231], v[90:93]
	v_mfma_f32_16x16x32_bf16 v[110:113], v[150:153], v[166:169], v[110:113]
	v_mfma_f32_16x16x32_bf16 v[78:81], v[158:161], v[166:169], v[78:81]
	v_mfma_f32_16x16x32_bf16 v[106:109], v[150:153], v[196:199], v[106:109]
	v_mfma_f32_16x16x32_bf16 v[74:77], v[158:161], v[196:199], v[74:77]
	v_mfma_f32_16x16x32_bf16 v[102:105], v[150:153], v[204:207], v[102:105]
	v_mfma_f32_16x16x32_bf16 v[70:73], v[158:161], v[204:207], v[70:73]
	v_mfma_f32_16x16x32_bf16 v[98:101], v[150:153], v[228:231], v[98:101]
	v_mfma_f32_16x16x32_bf16 v[66:69], v[158:161], v[228:231], v[66:69]
	s_setprio 0
	s_barrier
	s_add_i32 s0, s60, s31
	v_lshl_add_u64 v[208:209], s[6:7], 0, v[182:183]
	s_mov_b32 m0, s0
	ds_read_b128 v[162:165], v222 offset:16384
	ds_read_b128 v[166:169], v222 offset:17408
	ds_read_b128 v[192:195], v222 offset:18432
	ds_read_b128 v[196:199], v222 offset:19456
	ds_read_b128 v[200:203], v222 offset:20480
	ds_read_b128 v[204:207], v222 offset:21504
	ds_read_b128 v[224:227], v222 offset:22528
	ds_read_b128 v[228:231], v222 offset:23552
	global_load_lds_dwordx4 v[208:209], off
	s_add_i32 m0, s0, 0x2000
	s_add_u32 s0, s6, 0x100000
	v_lshl_add_u64 v[232:233], s[6:7], 0, v[186:187]
	s_addc_u32 s1, s7, 0
	s_add_i32 s38, s54, s31
	global_load_lds_dwordx4 v[232:233], off
	v_lshl_add_u64 v[234:235], s[0:1], 0, v[182:183]
	s_mov_b32 m0, s38
	v_lshl_add_u64 v[236:237], vcc, 0, v[184:185]
	global_load_lds_dwordx4 v[234:235], off
	v_lshl_add_u64 v[234:235], s[0:1], 0, v[186:187]
	s_add_i32 m0, s38, 0x2000
	s_nop 0
	global_load_lds_dwordx4 v[234:235], off
	v_lshl_add_u64 v[234:235], vcc, 0, v[180:181]
	s_mov_b32 m0, s9
	s_nop 0
	global_load_lds_dwordx4 v[234:235], off
	s_mov_b32 m0, s33
	s_nop 0
	global_load_lds_dwordx4 v[236:237], off
	s_waitcnt vmcnt(8)
	s_waitcnt lgkmcnt(0)
	s_barrier
	s_setprio 1
	s_waitcnt lgkmcnt(0)
	s_nop 0
	v_mfma_f32_16x16x32_bf16 v[54:57], v[130:133], v[162:165], v[54:57]
	v_mfma_f32_16x16x32_bf16 v[22:25], v[138:141], v[162:165], v[22:25]
	v_mfma_f32_16x16x32_bf16 v[50:53], v[130:133], v[192:195], v[50:53]
	v_mfma_f32_16x16x32_bf16 v[18:21], v[138:141], v[192:195], v[18:21]
	v_mfma_f32_16x16x32_bf16 v[62:65], v[130:133], v[200:203], v[62:65]
	v_mfma_f32_16x16x32_bf16 v[30:33], v[138:141], v[200:203], v[30:33]
	v_mfma_f32_16x16x32_bf16 v[58:61], v[130:133], v[224:227], v[58:61]
	v_mfma_f32_16x16x32_bf16 v[26:29], v[138:141], v[224:227], v[26:29]
	v_mfma_f32_16x16x32_bf16 v[46:49], v[146:149], v[162:165], v[46:49]
	v_mfma_f32_16x16x32_bf16 v[14:17], v[154:157], v[162:165], v[14:17]
	v_mfma_f32_16x16x32_bf16 v[42:45], v[146:149], v[192:195], v[42:45]
	v_mfma_f32_16x16x32_bf16 v[10:13], v[154:157], v[192:195], v[10:13]
	v_mfma_f32_16x16x32_bf16 v[38:41], v[146:149], v[200:203], v[38:41]
	v_mfma_f32_16x16x32_bf16 v[6:9], v[154:157], v[200:203], v[6:9]
	v_mfma_f32_16x16x32_bf16 v[34:37], v[146:149], v[224:227], v[34:37]
	v_mfma_f32_16x16x32_bf16 v[2:5], v[154:157], v[224:227], v[2:5]
	v_mfma_f32_16x16x32_bf16 v[54:57], v[134:137], v[166:169], v[54:57]
	v_mfma_f32_16x16x32_bf16 v[22:25], v[142:145], v[166:169], v[22:25]
	v_mfma_f32_16x16x32_bf16 v[50:53], v[134:137], v[196:199], v[50:53]
	v_mfma_f32_16x16x32_bf16 v[18:21], v[142:145], v[196:199], v[18:21]
	v_mfma_f32_16x16x32_bf16 v[62:65], v[134:137], v[204:207], v[62:65]
	v_mfma_f32_16x16x32_bf16 v[30:33], v[142:145], v[204:207], v[30:33]
	v_mfma_f32_16x16x32_bf16 v[58:61], v[134:137], v[228:231], v[58:61]
	v_mfma_f32_16x16x32_bf16 v[26:29], v[142:145], v[228:231], v[26:29]
	v_mfma_f32_16x16x32_bf16 v[46:49], v[150:153], v[166:169], v[46:49]
	v_mfma_f32_16x16x32_bf16 v[14:17], v[158:161], v[166:169], v[14:17]
	v_mfma_f32_16x16x32_bf16 v[42:45], v[150:153], v[196:199], v[42:45]
	v_mfma_f32_16x16x32_bf16 v[10:13], v[158:161], v[196:199], v[10:13]
	v_mfma_f32_16x16x32_bf16 v[38:41], v[150:153], v[204:207], v[38:41]
	v_mfma_f32_16x16x32_bf16 v[6:9], v[158:161], v[204:207], v[6:9]
	v_mfma_f32_16x16x32_bf16 v[34:37], v[150:153], v[228:231], v[34:37]
	v_mfma_f32_16x16x32_bf16 v[2:5], v[158:161], v[228:231], v[2:5]
	s_setprio 0
	s_barrier
	v_add_u32_e32 v0, s61, v221
	ds_read_b128 v[130:133], v0
	ds_read_b128 v[134:137], v0 offset:1024
	ds_read_b128 v[138:141], v0 offset:2048
	ds_read_b128 v[142:145], v0 offset:3072
	v_add_u32_e32 v0, s62, v221
	ds_read_b128 v[146:149], v0
	ds_read_b128 v[150:153], v0 offset:1024
	ds_read_b128 v[154:157], v0 offset:2048
	ds_read_b128 v[158:161], v0 offset:3072
	s_add_u32 s0, vcc_lo, 0x100000
	s_addc_u32 s1, vcc_hi, 0
	s_mov_b32 m0, s52
	v_lshl_add_u64 v[238:239], s[0:1], 0, v[180:181]
	ds_read_b128 v[162:165], v222 offset:32768
	ds_read_b128 v[166:169], v222 offset:33792
	ds_read_b128 v[192:195], v222 offset:34816
	ds_read_b128 v[196:199], v222 offset:35840
	ds_read_b128 v[200:203], v222 offset:36864
	ds_read_b128 v[204:207], v222 offset:37888
	ds_read_b128 v[224:227], v222 offset:38912
	ds_read_b128 v[228:231], v222 offset:39936
	global_load_lds_dwordx4 v[238:239], off
	v_lshl_add_u64 v[238:239], s[0:1], 0, v[184:185]
	s_mov_b32 m0, s53
	s_nop 0
	global_load_lds_dwordx4 v[238:239], off
	s_waitcnt vmcnt(8)
	s_waitcnt lgkmcnt(0)
	s_barrier
	s_setprio 1
	s_waitcnt lgkmcnt(0)
	s_nop 0
	v_mfma_f32_16x16x32_bf16 v[118:121], v[130:133], v[162:165], v[118:121]
	v_mfma_f32_16x16x32_bf16 v[86:89], v[138:141], v[162:165], v[86:89]
	v_mfma_f32_16x16x32_bf16 v[114:117], v[130:133], v[192:195], v[114:117]
	v_mfma_f32_16x16x32_bf16 v[82:85], v[138:141], v[192:195], v[82:85]
	v_mfma_f32_16x16x32_bf16 v[126:129], v[130:133], v[200:203], v[126:129]
	v_mfma_f32_16x16x32_bf16 v[94:97], v[138:141], v[200:203], v[94:97]
	v_mfma_f32_16x16x32_bf16 v[122:125], v[130:133], v[224:227], v[122:125]
	v_mfma_f32_16x16x32_bf16 v[90:93], v[138:141], v[224:227], v[90:93]
	v_mfma_f32_16x16x32_bf16 v[110:113], v[146:149], v[162:165], v[110:113]
	v_mfma_f32_16x16x32_bf16 v[78:81], v[154:157], v[162:165], v[78:81]
	v_mfma_f32_16x16x32_bf16 v[106:109], v[146:149], v[192:195], v[106:109]
	v_mfma_f32_16x16x32_bf16 v[74:77], v[154:157], v[192:195], v[74:77]
	v_mfma_f32_16x16x32_bf16 v[102:105], v[146:149], v[200:203], v[102:105]
	v_mfma_f32_16x16x32_bf16 v[70:73], v[154:157], v[200:203], v[70:73]
	v_mfma_f32_16x16x32_bf16 v[98:101], v[146:149], v[224:227], v[98:101]
	v_mfma_f32_16x16x32_bf16 v[66:69], v[154:157], v[224:227], v[66:69]
	v_mfma_f32_16x16x32_bf16 v[118:121], v[134:137], v[166:169], v[118:121]
	v_mfma_f32_16x16x32_bf16 v[86:89], v[142:145], v[166:169], v[86:89]
	v_mfma_f32_16x16x32_bf16 v[114:117], v[134:137], v[196:199], v[114:117]
	v_mfma_f32_16x16x32_bf16 v[82:85], v[142:145], v[196:199], v[82:85]
	v_mfma_f32_16x16x32_bf16 v[126:129], v[134:137], v[204:207], v[126:129]
	v_mfma_f32_16x16x32_bf16 v[94:97], v[142:145], v[204:207], v[94:97]
	v_mfma_f32_16x16x32_bf16 v[122:125], v[134:137], v[228:231], v[122:125]
	v_mfma_f32_16x16x32_bf16 v[90:93], v[142:145], v[228:231], v[90:93]
	v_mfma_f32_16x16x32_bf16 v[110:113], v[150:153], v[166:169], v[110:113]
	v_mfma_f32_16x16x32_bf16 v[78:81], v[158:161], v[166:169], v[78:81]
	v_mfma_f32_16x16x32_bf16 v[106:109], v[150:153], v[196:199], v[106:109]
	v_mfma_f32_16x16x32_bf16 v[74:77], v[158:161], v[196:199], v[74:77]
	v_mfma_f32_16x16x32_bf16 v[102:105], v[150:153], v[204:207], v[102:105]
	v_mfma_f32_16x16x32_bf16 v[70:73], v[158:161], v[204:207], v[70:73]
	v_mfma_f32_16x16x32_bf16 v[98:101], v[150:153], v[228:231], v[98:101]
	v_mfma_f32_16x16x32_bf16 v[66:69], v[158:161], v[228:231], v[66:69]
	s_setprio 0
	s_barrier
	s_add_i32 s0, s61, s31
	v_lshl_add_u64 v[208:209], v[208:209], 0, s[88:89]
	s_mov_b32 m0, s0
	ds_read_b128 v[162:165], v222 offset:49152
	ds_read_b128 v[166:169], v222 offset:50176
	ds_read_b128 v[192:195], v222 offset:51200
	ds_read_b128 v[196:199], v222 offset:52224
	ds_read_b128 v[200:203], v222 offset:53248
	ds_read_b128 v[204:207], v222 offset:54272
	ds_read_b128 v[224:227], v222 offset:55296
	ds_read_b128 v[228:231], v222 offset:56320
	global_load_lds_dwordx4 v[208:209], off
	s_add_i32 m0, s0, 0x2000
	s_add_u32 s0, s6, 0x100080
	v_lshl_add_u64 v[208:209], v[232:233], 0, s[88:89]
	s_addc_u32 s1, s7, 0
	s_add_i32 s6, s62, s31
	global_load_lds_dwordx4 v[208:209], off
	v_lshl_add_u64 v[208:209], s[0:1], 0, v[182:183]
	s_mov_b32 m0, s6
	s_nop 0
	global_load_lds_dwordx4 v[208:209], off
	v_lshl_add_u64 v[208:209], s[0:1], 0, v[186:187]
	s_add_i32 m0, s6, 0x2000
	s_nop 0
	global_load_lds_dwordx4 v[208:209], off
	v_lshl_add_u64 v[208:209], v[234:235], 0, s[88:89]
	s_mov_b32 m0, s63
	s_nop 0
	global_load_lds_dwordx4 v[208:209], off
	v_lshl_add_u64 v[208:209], v[236:237], 0, s[88:89]
	s_mov_b32 m0, s90
	s_nop 0
	global_load_lds_dwordx4 v[208:209], off
	s_waitcnt vmcnt(8)
	s_waitcnt lgkmcnt(0)
	s_barrier
	s_setprio 1
	s_waitcnt lgkmcnt(0)
	v_mfma_f32_16x16x32_bf16 v[54:57], v[130:133], v[162:165], v[54:57]
	v_mfma_f32_16x16x32_bf16 v[22:25], v[138:141], v[162:165], v[22:25]
	v_mfma_f32_16x16x32_bf16 v[50:53], v[130:133], v[192:195], v[50:53]
	v_mfma_f32_16x16x32_bf16 v[18:21], v[138:141], v[192:195], v[18:21]
	v_mfma_f32_16x16x32_bf16 v[62:65], v[130:133], v[200:203], v[62:65]
	v_mfma_f32_16x16x32_bf16 v[30:33], v[138:141], v[200:203], v[30:33]
	v_mfma_f32_16x16x32_bf16 v[58:61], v[130:133], v[224:227], v[58:61]
	v_mfma_f32_16x16x32_bf16 v[26:29], v[138:141], v[224:227], v[26:29]
	v_mfma_f32_16x16x32_bf16 v[46:49], v[146:149], v[162:165], v[46:49]
	v_mfma_f32_16x16x32_bf16 v[14:17], v[154:157], v[162:165], v[14:17]
	v_mfma_f32_16x16x32_bf16 v[42:45], v[146:149], v[192:195], v[42:45]
	v_mfma_f32_16x16x32_bf16 v[10:13], v[154:157], v[192:195], v[10:13]
	v_mfma_f32_16x16x32_bf16 v[38:41], v[146:149], v[200:203], v[38:41]
	v_mfma_f32_16x16x32_bf16 v[6:9], v[154:157], v[200:203], v[6:9]
	v_mfma_f32_16x16x32_bf16 v[34:37], v[146:149], v[224:227], v[34:37]
	v_mfma_f32_16x16x32_bf16 v[2:5], v[154:157], v[224:227], v[2:5]
	v_mfma_f32_16x16x32_bf16 v[54:57], v[134:137], v[166:169], v[54:57]
	v_mfma_f32_16x16x32_bf16 v[22:25], v[142:145], v[166:169], v[22:25]
	v_mfma_f32_16x16x32_bf16 v[50:53], v[134:137], v[196:199], v[50:53]
	v_mfma_f32_16x16x32_bf16 v[18:21], v[142:145], v[196:199], v[18:21]
	v_mfma_f32_16x16x32_bf16 v[62:65], v[134:137], v[204:207], v[62:65]
	v_mfma_f32_16x16x32_bf16 v[30:33], v[142:145], v[204:207], v[30:33]
	v_mfma_f32_16x16x32_bf16 v[58:61], v[134:137], v[228:231], v[58:61]
	v_mfma_f32_16x16x32_bf16 v[26:29], v[142:145], v[228:231], v[26:29]
	v_mfma_f32_16x16x32_bf16 v[46:49], v[150:153], v[166:169], v[46:49]
	v_mfma_f32_16x16x32_bf16 v[14:17], v[158:161], v[166:169], v[14:17]
	v_mfma_f32_16x16x32_bf16 v[42:45], v[150:153], v[196:199], v[42:45]
	v_mfma_f32_16x16x32_bf16 v[10:13], v[158:161], v[196:199], v[10:13]
	v_mfma_f32_16x16x32_bf16 v[38:41], v[150:153], v[204:207], v[38:41]
	v_mfma_f32_16x16x32_bf16 v[6:9], v[158:161], v[204:207], v[6:9]
	v_mfma_f32_16x16x32_bf16 v[34:37], v[150:153], v[228:231], v[34:37]
	v_mfma_f32_16x16x32_bf16 v[2:5], v[158:161], v[228:231], v[2:5]
	s_setprio 0
	s_barrier
	s_add_i32 s37, s37, 2
	s_add_u32 s3, s3, 0x100
	s_addc_u32 s36, s36, 0
	s_cmp_gt_u32 s37, 61
	s_mov_b64 s[0:1], s[4:5]
	s_cbranch_scc0 .LBB0_883
	s_and_b64 vcc, exec, s[94:95]
	s_cbranch_vccz .LBB0_886
	s_barrier

.LBB0_1170:
	v_add_u32_e32 v148, s60, v152
	ds_read_b128 v[144:147], v148
	ds_read_b128 v[154:157], v148 offset:1024
	ds_read_b128 v[158:161], v148 offset:2048
	ds_read_b128 v[162:165], v148 offset:3072
	v_add_u32_e32 v148, s54, v152
	ds_read_b128 v[166:169], v148
	ds_read_b128 v[180:183], v148 offset:1024
	ds_read_b128 v[184:187], v148 offset:2048
	ds_read_b128 v[188:191], v148 offset:3072
	s_add_u32 s36, s10, s2
	s_addc_u32 s37, s11, s3
	s_add_u32 s38, s4, s2
	s_addc_u32 s39, s5, s3
	s_cmp_eq_u32 s31, s13
	s_cselect_b32 s67, s19, s37
	s_cselect_b32 s66, s18, s36
	s_cselect_b32 s65, s35, s39
	s_cselect_b32 s64, s34, s38
	v_lshl_add_u64 v[148:149], s[10:11], 0, v[132:133]
	s_add_i32 m0, s23, 0xc000
	ds_read_b128 v[192:195], v153
	ds_read_b128 v[196:199], v153 offset:1024
	ds_read_b128 v[200:203], v153 offset:2048
	ds_read_b128 v[204:207], v153 offset:3072
	ds_read_b128 v[218:221], v153 offset:4096
	ds_read_b128 v[222:225], v153 offset:5120
	ds_read_b128 v[226:229], v153 offset:6144
	ds_read_b128 v[230:233], v153 offset:7168
	global_load_lds_dwordx4 v[148:149], off
	v_lshl_add_u64 v[148:149], s[10:11], 0, v[130:131]
	s_add_i32 m0, s23, 0xe000
	s_nop 0
	global_load_lds_dwordx4 v[148:149], off
	s_waitcnt vmcnt(8)
	s_waitcnt lgkmcnt(0)
	s_barrier
	s_setprio 1
	s_waitcnt lgkmcnt(0)
	v_mfma_f32_16x16x32_bf16 v[126:129], v[144:147], v[192:195], v[126:129]
	v_mfma_f32_16x16x32_bf16 v[122:125], v[158:161], v[192:195], v[122:125]
	v_mfma_f32_16x16x32_bf16 v[118:121], v[144:147], v[200:203], v[118:121]
	v_mfma_f32_16x16x32_bf16 v[114:117], v[158:161], v[200:203], v[114:117]
	v_mfma_f32_16x16x32_bf16 v[110:113], v[144:147], v[218:221], v[110:113]
	v_mfma_f32_16x16x32_bf16 v[106:109], v[158:161], v[218:221], v[106:109]
	v_mfma_f32_16x16x32_bf16 v[102:105], v[144:147], v[226:229], v[102:105]
	v_mfma_f32_16x16x32_bf16 v[98:101], v[158:161], v[226:229], v[98:101]
	v_mfma_f32_16x16x32_bf16 v[94:97], v[166:169], v[192:195], v[94:97]
	v_mfma_f32_16x16x32_bf16 v[90:93], v[184:187], v[192:195], v[90:93]
	v_mfma_f32_16x16x32_bf16 v[86:89], v[166:169], v[200:203], v[86:89]
	v_mfma_f32_16x16x32_bf16 v[82:85], v[184:187], v[200:203], v[82:85]
	v_mfma_f32_16x16x32_bf16 v[78:81], v[166:169], v[218:221], v[78:81]
	v_mfma_f32_16x16x32_bf16 v[74:77], v[184:187], v[218:221], v[74:77]
	v_mfma_f32_16x16x32_bf16 v[70:73], v[166:169], v[226:229], v[70:73]
	v_mfma_f32_16x16x32_bf16 v[66:69], v[184:187], v[226:229], v[66:69]
	v_mfma_f32_16x16x32_bf16 v[126:129], v[154:157], v[196:199], v[126:129]
	v_mfma_f32_16x16x32_bf16 v[122:125], v[162:165], v[196:199], v[122:125]
	v_mfma_f32_16x16x32_bf16 v[118:121], v[154:157], v[204:207], v[118:121]
	v_mfma_f32_16x16x32_bf16 v[114:117], v[162:165], v[204:207], v[114:117]
	v_mfma_f32_16x16x32_bf16 v[110:113], v[154:157], v[222:225], v[110:113]
	v_mfma_f32_16x16x32_bf16 v[106:109], v[162:165], v[222:225], v[106:109]
	v_mfma_f32_16x16x32_bf16 v[102:105], v[154:157], v[230:233], v[102:105]
	v_mfma_f32_16x16x32_bf16 v[98:101], v[162:165], v[230:233], v[98:101]
	v_mfma_f32_16x16x32_bf16 v[94:97], v[180:183], v[196:199], v[94:97]
	v_mfma_f32_16x16x32_bf16 v[90:93], v[188:191], v[196:199], v[90:93]
	v_mfma_f32_16x16x32_bf16 v[86:89], v[180:183], v[204:207], v[86:89]
	v_mfma_f32_16x16x32_bf16 v[82:85], v[188:191], v[204:207], v[82:85]
	v_mfma_f32_16x16x32_bf16 v[78:81], v[180:183], v[222:225], v[78:81]
	v_mfma_f32_16x16x32_bf16 v[74:77], v[188:191], v[222:225], v[74:77]
	v_mfma_f32_16x16x32_bf16 v[70:73], v[180:183], v[230:233], v[70:73]
	v_mfma_f32_16x16x32_bf16 v[66:69], v[188:191], v[230:233], v[66:69]
	s_setprio 0
	s_barrier
	s_add_i32 s36, s60, s22
	v_lshl_add_u64 v[148:149], s[64:65], 0, v[0:1]
	s_mov_b32 m0, s36
	ds_read_b128 v[192:195], v153 offset:16384
	ds_read_b128 v[196:199], v153 offset:17408
	ds_read_b128 v[200:203], v153 offset:18432
	ds_read_b128 v[204:207], v153 offset:19456
	ds_read_b128 v[218:221], v153 offset:20480
	ds_read_b128 v[222:225], v153 offset:21504
	ds_read_b128 v[226:229], v153 offset:22528
	ds_read_b128 v[230:233], v153 offset:23552
	global_load_lds_dwordx4 v[148:149], off
	s_add_i32 m0, s36, 0x2000
	s_add_u32 s36, s64, 0x2b0000
	v_lshl_add_u64 v[208:209], s[64:65], 0, v[138:139]
	s_addc_u32 s37, s65, 0
	s_add_i32 s38, s54, s22
	global_load_lds_dwordx4 v[208:209], off
	v_lshl_add_u64 v[234:235], s[36:37], 0, v[0:1]
	s_mov_b32 m0, s38
	v_lshl_add_u64 v[236:237], s[66:67], 0, v[136:137]
	global_load_lds_dwordx4 v[234:235], off
	v_lshl_add_u64 v[234:235], s[36:37], 0, v[138:139]
	s_add_i32 m0, s38, 0x2000
	s_nop 0
	global_load_lds_dwordx4 v[234:235], off
	v_lshl_add_u64 v[234:235], s[66:67], 0, v[134:135]
	s_mov_b32 m0, s23
	s_nop 0
	global_load_lds_dwordx4 v[234:235], off
	s_mov_b32 m0, s24
	s_nop 0
	global_load_lds_dwordx4 v[236:237], off
	s_waitcnt vmcnt(8)
	s_waitcnt lgkmcnt(0)
	s_barrier
	s_setprio 1
	s_waitcnt lgkmcnt(0)
	s_nop 0
	v_mfma_f32_16x16x32_bf16 v[62:65], v[144:147], v[192:195], v[62:65]
	v_mfma_f32_16x16x32_bf16 v[58:61], v[158:161], v[192:195], v[58:61]
	v_mfma_f32_16x16x32_bf16 v[54:57], v[144:147], v[200:203], v[54:57]
	v_mfma_f32_16x16x32_bf16 v[50:53], v[158:161], v[200:203], v[50:53]
	v_mfma_f32_16x16x32_bf16 v[46:49], v[144:147], v[218:221], v[46:49]
	v_mfma_f32_16x16x32_bf16 v[42:45], v[158:161], v[218:221], v[42:45]
	v_mfma_f32_16x16x32_bf16 v[38:41], v[144:147], v[226:229], v[38:41]
	v_mfma_f32_16x16x32_bf16 v[34:37], v[158:161], v[226:229], v[34:37]
	v_mfma_f32_16x16x32_bf16 v[30:33], v[166:169], v[192:195], v[30:33]
	v_mfma_f32_16x16x32_bf16 v[26:29], v[184:187], v[192:195], v[26:29]
	v_mfma_f32_16x16x32_bf16 v[22:25], v[166:169], v[200:203], v[22:25]
	v_mfma_f32_16x16x32_bf16 v[18:21], v[184:187], v[200:203], v[18:21]
	v_mfma_f32_16x16x32_bf16 v[14:17], v[166:169], v[218:221], v[14:17]
	v_mfma_f32_16x16x32_bf16 v[10:13], v[184:187], v[218:221], v[10:13]
	v_mfma_f32_16x16x32_bf16 v[6:9], v[166:169], v[226:229], v[6:9]
	v_mfma_f32_16x16x32_bf16 v[2:5], v[184:187], v[226:229], v[2:5]
	v_mfma_f32_16x16x32_bf16 v[62:65], v[154:157], v[196:199], v[62:65]
	v_mfma_f32_16x16x32_bf16 v[58:61], v[162:165], v[196:199], v[58:61]
	v_mfma_f32_16x16x32_bf16 v[54:57], v[154:157], v[204:207], v[54:57]
	v_mfma_f32_16x16x32_bf16 v[50:53], v[162:165], v[204:207], v[50:53]
	v_mfma_f32_16x16x32_bf16 v[46:49], v[154:157], v[222:225], v[46:49]
	v_mfma_f32_16x16x32_bf16 v[42:45], v[162:165], v[222:225], v[42:45]
	v_mfma_f32_16x16x32_bf16 v[38:41], v[154:157], v[230:233], v[38:41]
	v_mfma_f32_16x16x32_bf16 v[34:37], v[162:165], v[230:233], v[34:37]
	v_mfma_f32_16x16x32_bf16 v[30:33], v[180:183], v[196:199], v[30:33]
	v_mfma_f32_16x16x32_bf16 v[26:29], v[188:191], v[196:199], v[26:29]
	v_mfma_f32_16x16x32_bf16 v[22:25], v[180:183], v[204:207], v[22:25]
	v_mfma_f32_16x16x32_bf16 v[18:21], v[188:191], v[204:207], v[18:21]
	v_mfma_f32_16x16x32_bf16 v[14:17], v[180:183], v[222:225], v[14:17]
	v_mfma_f32_16x16x32_bf16 v[10:13], v[188:191], v[222:225], v[10:13]
	v_mfma_f32_16x16x32_bf16 v[6:9], v[180:183], v[230:233], v[6:9]
	v_mfma_f32_16x16x32_bf16 v[2:5], v[188:191], v[230:233], v[2:5]
	s_setprio 0
	s_barrier
	v_add_u32_e32 v162, s61, v152
	v_add_u32_e32 v170, s62, v152
	ds_read_b128 v[144:147], v162
	ds_read_b128 v[154:157], v162 offset:1024
	ds_read_b128 v[158:161], v162 offset:2048
	ds_read_b128 v[162:165], v162 offset:3072
	ds_read_b128 v[166:169], v170
	ds_read_b128 v[180:183], v170 offset:1024
	ds_read_b128 v[184:187], v170 offset:2048
	ds_read_b128 v[188:191], v170 offset:3072
	s_add_u32 s36, s66, 0x2b0000
	s_addc_u32 s37, s67, 0
	s_mov_b32 m0, s25
	v_lshl_add_u64 v[238:239], s[36:37], 0, v[134:135]
	ds_read_b128 v[192:195], v153 offset:32768
	ds_read_b128 v[196:199], v153 offset:33792
	ds_read_b128 v[200:203], v153 offset:34816
	ds_read_b128 v[204:207], v153 offset:35840
	ds_read_b128 v[218:221], v153 offset:36864
	ds_read_b128 v[222:225], v153 offset:37888
	ds_read_b128 v[226:229], v153 offset:38912
	ds_read_b128 v[230:233], v153 offset:39936
	global_load_lds_dwordx4 v[238:239], off
	v_lshl_add_u64 v[238:239], s[36:37], 0, v[136:137]
	s_mov_b32 m0, s26
	s_nop 0
	global_load_lds_dwordx4 v[238:239], off
	s_waitcnt vmcnt(8)
	s_waitcnt lgkmcnt(0)
	s_barrier
	s_setprio 1
	s_waitcnt lgkmcnt(0)
	s_nop 0
	v_mfma_f32_16x16x32_bf16 v[126:129], v[144:147], v[192:195], v[126:129]
	v_mfma_f32_16x16x32_bf16 v[122:125], v[158:161], v[192:195], v[122:125]
	v_mfma_f32_16x16x32_bf16 v[118:121], v[144:147], v[200:203], v[118:121]
	v_mfma_f32_16x16x32_bf16 v[114:117], v[158:161], v[200:203], v[114:117]
	v_mfma_f32_16x16x32_bf16 v[110:113], v[144:147], v[218:221], v[110:113]
	v_mfma_f32_16x16x32_bf16 v[106:109], v[158:161], v[218:221], v[106:109]
	v_mfma_f32_16x16x32_bf16 v[102:105], v[144:147], v[226:229], v[102:105]
	v_mfma_f32_16x16x32_bf16 v[98:101], v[158:161], v[226:229], v[98:101]
	v_mfma_f32_16x16x32_bf16 v[94:97], v[166:169], v[192:195], v[94:97]
	v_mfma_f32_16x16x32_bf16 v[90:93], v[184:187], v[192:195], v[90:93]
	v_mfma_f32_16x16x32_bf16 v[86:89], v[166:169], v[200:203], v[86:89]
	v_mfma_f32_16x16x32_bf16 v[82:85], v[184:187], v[200:203], v[82:85]
	v_mfma_f32_16x16x32_bf16 v[78:81], v[166:169], v[218:221], v[78:81]
	v_mfma_f32_16x16x32_bf16 v[74:77], v[184:187], v[218:221], v[74:77]
	v_mfma_f32_16x16x32_bf16 v[70:73], v[166:169], v[226:229], v[70:73]
	v_mfma_f32_16x16x32_bf16 v[66:69], v[184:187], v[226:229], v[66:69]
	v_mfma_f32_16x16x32_bf16 v[126:129], v[154:157], v[196:199], v[126:129]
	v_mfma_f32_16x16x32_bf16 v[122:125], v[162:165], v[196:199], v[122:125]
	v_mfma_f32_16x16x32_bf16 v[118:121], v[154:157], v[204:207], v[118:121]
	v_mfma_f32_16x16x32_bf16 v[114:117], v[162:165], v[204:207], v[114:117]
	v_mfma_f32_16x16x32_bf16 v[110:113], v[154:157], v[222:225], v[110:113]
	v_mfma_f32_16x16x32_bf16 v[106:109], v[162:165], v[222:225], v[106:109]
	v_mfma_f32_16x16x32_bf16 v[102:105], v[154:157], v[230:233], v[102:105]
	v_mfma_f32_16x16x32_bf16 v[98:101], v[162:165], v[230:233], v[98:101]
	v_mfma_f32_16x16x32_bf16 v[94:97], v[180:183], v[196:199], v[94:97]
	v_mfma_f32_16x16x32_bf16 v[90:93], v[188:191], v[196:199], v[90:93]
	v_mfma_f32_16x16x32_bf16 v[86:89], v[180:183], v[204:207], v[86:89]
	v_mfma_f32_16x16x32_bf16 v[82:85], v[188:191], v[204:207], v[82:85]
	v_mfma_f32_16x16x32_bf16 v[78:81], v[180:183], v[222:225], v[78:81]
	v_mfma_f32_16x16x32_bf16 v[74:77], v[188:191], v[222:225], v[74:77]
	v_mfma_f32_16x16x32_bf16 v[70:73], v[180:183], v[230:233], v[70:73]
	v_mfma_f32_16x16x32_bf16 v[66:69], v[188:191], v[230:233], v[66:69]
	s_setprio 0
	s_barrier
	s_add_i32 s36, s61, s22
	v_lshl_add_u64 v[148:149], v[148:149], 0, s[88:89]
	s_mov_b32 m0, s36
	ds_read_b128 v[192:195], v153 offset:49152
	ds_read_b128 v[196:199], v153 offset:50176
	ds_read_b128 v[200:203], v153 offset:51200
	ds_read_b128 v[204:207], v153 offset:52224
	ds_read_b128 v[218:221], v153 offset:53248
	ds_read_b128 v[222:225], v153 offset:54272
	ds_read_b128 v[226:229], v153 offset:55296
	ds_read_b128 v[230:233], v153 offset:56320
	global_load_lds_dwordx4 v[148:149], off
	s_add_i32 m0, s36, 0x2000
	s_add_u32 s36, s64, 0x2b0080
	v_lshl_add_u64 v[148:149], v[208:209], 0, s[88:89]
	s_addc_u32 s37, s65, 0
	s_add_i32 s38, s62, s22
	global_load_lds_dwordx4 v[148:149], off
	v_lshl_add_u64 v[148:149], s[36:37], 0, v[0:1]
	s_mov_b32 m0, s38
	s_nop 0
	global_load_lds_dwordx4 v[148:149], off
	v_lshl_add_u64 v[148:149], s[36:37], 0, v[138:139]
	s_add_i32 m0, s38, 0x2000
	s_nop 0
	global_load_lds_dwordx4 v[148:149], off
	v_lshl_add_u64 v[148:149], v[234:235], 0, s[88:89]
	s_mov_b32 m0, s29
	s_nop 0
	global_load_lds_dwordx4 v[148:149], off
	v_lshl_add_u64 v[148:149], v[236:237], 0, s[88:89]
	s_mov_b32 m0, s30
	s_nop 0
	global_load_lds_dwordx4 v[148:149], off
	s_waitcnt vmcnt(8)
	s_waitcnt lgkmcnt(0)
	s_barrier
	s_setprio 1
	s_waitcnt lgkmcnt(0)
	v_mfma_f32_16x16x32_bf16 v[62:65], v[144:147], v[192:195], v[62:65]
	v_mfma_f32_16x16x32_bf16 v[58:61], v[158:161], v[192:195], v[58:61]
	v_mfma_f32_16x16x32_bf16 v[54:57], v[144:147], v[200:203], v[54:57]
	v_mfma_f32_16x16x32_bf16 v[50:53], v[158:161], v[200:203], v[50:53]
	v_mfma_f32_16x16x32_bf16 v[46:49], v[144:147], v[218:221], v[46:49]
	v_mfma_f32_16x16x32_bf16 v[42:45], v[158:161], v[218:221], v[42:45]
	v_mfma_f32_16x16x32_bf16 v[38:41], v[144:147], v[226:229], v[38:41]
	v_mfma_f32_16x16x32_bf16 v[34:37], v[158:161], v[226:229], v[34:37]
	v_mfma_f32_16x16x32_bf16 v[30:33], v[166:169], v[192:195], v[30:33]
	v_mfma_f32_16x16x32_bf16 v[26:29], v[184:187], v[192:195], v[26:29]
	v_mfma_f32_16x16x32_bf16 v[22:25], v[166:169], v[200:203], v[22:25]
	v_mfma_f32_16x16x32_bf16 v[18:21], v[184:187], v[200:203], v[18:21]
	v_mfma_f32_16x16x32_bf16 v[14:17], v[166:169], v[218:221], v[14:17]
	v_mfma_f32_16x16x32_bf16 v[10:13], v[184:187], v[218:221], v[10:13]
	v_mfma_f32_16x16x32_bf16 v[6:9], v[166:169], v[226:229], v[6:9]
	v_mfma_f32_16x16x32_bf16 v[2:5], v[184:187], v[226:229], v[2:5]
	v_mfma_f32_16x16x32_bf16 v[62:65], v[154:157], v[196:199], v[62:65]
	v_mfma_f32_16x16x32_bf16 v[58:61], v[162:165], v[196:199], v[58:61]
	v_mfma_f32_16x16x32_bf16 v[54:57], v[154:157], v[204:207], v[54:57]
	v_mfma_f32_16x16x32_bf16 v[50:53], v[162:165], v[204:207], v[50:53]
	v_mfma_f32_16x16x32_bf16 v[46:49], v[154:157], v[222:225], v[46:49]
	v_mfma_f32_16x16x32_bf16 v[42:45], v[162:165], v[222:225], v[42:45]
	v_mfma_f32_16x16x32_bf16 v[38:41], v[154:157], v[230:233], v[38:41]
	v_mfma_f32_16x16x32_bf16 v[34:37], v[162:165], v[230:233], v[34:37]
	v_mfma_f32_16x16x32_bf16 v[30:33], v[180:183], v[196:199], v[30:33]
	v_mfma_f32_16x16x32_bf16 v[26:29], v[188:191], v[196:199], v[26:29]
	v_mfma_f32_16x16x32_bf16 v[22:25], v[180:183], v[204:207], v[22:25]
	v_mfma_f32_16x16x32_bf16 v[18:21], v[188:191], v[204:207], v[18:21]
	v_mfma_f32_16x16x32_bf16 v[14:17], v[180:183], v[222:225], v[14:17]
	v_mfma_f32_16x16x32_bf16 v[10:13], v[188:191], v[222:225], v[10:13]
	v_mfma_f32_16x16x32_bf16 v[6:9], v[180:183], v[230:233], v[6:9]
	v_mfma_f32_16x16x32_bf16 v[2:5], v[188:191], v[230:233], v[2:5]
	s_setprio 0
	s_barrier
	s_add_i32 s36, s13, 2
	s_add_u32 s2, s2, 0x100
	s_addc_u32 s3, s3, 0
	v_lshl_add_u64 v[132:133], v[132:133], 0, s[92:93]
	v_lshl_add_u64 v[130:131], v[130:131], 0, s[92:93]
	s_cmp_ge_i32 s13, s31
	s_mov_b32 s13, s36
	s_cbranch_scc0 .LBB0_1170
	s_and_b64 vcc, exec, s[8:9]
	s_cbranch_vccz .LBB0_1173
	s_barrier
